# GLA chunk-B prefetch: compiler's row>=0 masked loads (112 instrs) -> nine direct loads with shared row address math (41 instrs), as for the chunk-A copy
# speedup vs baseline: 1.0111x; 1.0111x over previous
; __device__ __forceinline__ void gla_unit(const Params& p, const WS& ws, int u, bool dry = false) {
;     ...
;   auto prefetch = [&](int c, u32x4 (&qr)[4], u32x4 (&kr)[4], u32x4& vr, float (&ebl)[2]) {
;     const int tbase = 64 * c - 48;
; #pragma unroll
;     for (int i = 0; i < 4; ++i) {
;       const int ci = tid + 256 * i; const int row = ci >> 4, ch = ci & 15; const int t = tbase + row;
;       qr[i] = (u32x4){0, 0, 0, 0}; kr[i] = (u32x4){0, 0, 0, 0};
;       if (t >= 0) {
;         qr[i] = *(const u32x4*)(ws.Q + (size_t)(b * T_ + t) * 512 + hd * 128 + ch * 8);
;         kr[i] = *(const u32x4*)(ws.K + (size_t)(b * T_ + t) * 512 + hd * 128 + ch * 8);
;       }
;     }
;     {
;       const int row = tid >> 2, ch = tid & 3; const int t = tbase + row;
;       vr = (u32x4){0, 0, 0, 0};
;       if (t >= 0) vr = *(const u32x4*)(ws.V + (size_t)(b * T_ + t) * 1024 + hd * 256 + sl * 32 + ch * 8);
;     }
;     ebl[0] = BLp[c * 128 + 16 * (2 * w) + lr];
;     ebl[1] = BLp[c * 128 + 16 * (2 * w + 1) + lr];
;   };
.LBB0_1638:
	s_or_b64 exec, exec, s[12:13]
	s_cmp_gt_u32 s35, 30
	s_waitcnt vmcnt(0)
	v_mov_b32_e32 v179, v242
	v_mov_b32_e32 v204, v209
	v_mov_b32_e32 v242, v179
	v_mov_b32_e32 v209, v204
	s_cbranch_scc1 .LBB0_1650
	v_mov_b32_e32 v13, v12
	v_add_u32_e32 v100, s92, v202
	v_add_u32_e32 v100, 0x90, v100
	v_ashrrev_i32_e32 v101, 31, v100
	v_lshlrev_b64 v[100:101], 10, v[100:101]
	v_lshl_add_u64 v[14:15], v[132:133], 0, v[100:101]
	global_load_dwordx4 v[44:47], v[14:15], off
	v_lshl_add_u64 v[14:15], v[134:135], 0, v[100:101]
	global_load_dwordx4 v[48:51], v[14:15], off
	v_add_u32_e32 v100, s92, v201
	v_add_u32_e32 v100, 0x90, v100
	v_ashrrev_i32_e32 v101, 31, v100
	v_lshlrev_b64 v[100:101], 10, v[100:101]
	v_lshl_add_u64 v[14:15], v[132:133], 0, v[100:101]
	global_load_dwordx4 v[56:59], v[14:15], off
	v_lshl_add_u64 v[14:15], v[134:135], 0, v[100:101]
	global_load_dwordx4 v[52:55], v[14:15], off
	v_add_u32_e32 v100, s92, v185
	v_add_u32_e32 v100, 0x90, v100
	v_ashrrev_i32_e32 v101, 31, v100
	v_lshlrev_b64 v[100:101], 10, v[100:101]
	v_lshl_add_u64 v[14:15], v[132:133], 0, v[100:101]
	global_load_dwordx4 v[64:67], v[14:15], off
	v_lshl_add_u64 v[14:15], v[134:135], 0, v[100:101]
	global_load_dwordx4 v[68:71], v[14:15], off
	v_add_u32_e32 v100, s92, v184
	v_add_u32_e32 v100, 0x90, v100
	v_ashrrev_i32_e32 v101, 31, v100
	v_lshlrev_b64 v[100:101], 10, v[100:101]
	v_lshl_add_u64 v[14:15], v[132:133], 0, v[100:101]
	global_load_dwordx4 v[72:75], v[14:15], off
	v_lshl_add_u64 v[14:15], v[134:135], 0, v[100:101]
	global_load_dwordx4 v[76:79], v[14:15], off
	v_add_u32_e32 v100, s92, v183
	v_add_u32_e32 v100, 0x90, v100
	v_ashrrev_i32_e32 v101, 31, v100
	v_lshlrev_b64 v[100:101], 11, v[100:101]
	v_lshl_add_u64 v[14:15], v[136:137], 0, v[100:101]
	global_load_dwordx4 v[80:83], v[14:15], off
	global_load_dword v209, v[140:141], off offset:512
	global_load_dword v242, v[140:141], off offset:576
